# v16 + attention epilogue: 16 subln gain loads batched up front, per-store vmcnt(0) waits removed
# speedup vs baseline: 1.0095x; 1.0011x over previous
; __device__ __forceinline__ float swap32_sum(float m) { auto rr = __builtin_amdgcn_permlane32_swap(__float_as_uint(m), __float_as_uint(m), false, false); return __uint_as_float(rr[0]) + __uint_as_float(rr[1]); }
; template <bool FAST> __device__ __forceinline__ bool attn_unit(LAS unsigned char* lds, const bf16_t* QKV, bf16_t* O, int qrow0, int b, int h, int nt, float lam, float oscale, const float* subln_g) {
;     ...
;     if (map == 0) {
;         float ss = 0.f;
; #pragma unroll
;         for (int c = 0; c < 4; ++c)
; #pragma unroll
;             for (int i = 0; i < 16; ++i) { const float v = o[c][i] * inv - lam * ex[((wq * 64) + c * 16 + i) * 64 + lane]; o[c][i] = v; ss += v * v; }
;         ss = swap32_sum(ss);
;         const float r = rsqrtf(ss * (1.f / 128.f) + EPS) * oscale;
;         bf16_t* op = O + (size_t)(qrow0 + wq * 32 + r32) * D + h * 128;
; #pragma unroll
;         for (int c = 0; c < 4; ++c)
; #pragma unroll
;             for (int g4 = 0; g4 < 4; ++g4) { const int d = 32 * c + 8 * g4 + 4 * hi; const f32x4 gv = *(const f32x4*)(subln_g + d);
.LBB0_331:
	s_and_b64 vcc, exec, s[36:37]
	s_waitcnt lgkmcnt(0)
	s_barrier
	s_cbranch_vccnz .LBB0_268
	s_lshl_b32 s0, s78, 8
	v_lshl_add_u32 v2, v236, 2, 0
	s_and_b32 s10, s0, 0xc000
	v_add_u32_e32 v3, s10, v2
	ds_read2st64_b32 v[10:11], v3 offset1:1
	ds_read2st64_b32 v[8:9], v3 offset0:2 offset1:3
	ds_read2st64_b32 v[102:103], v3 offset0:4 offset1:5
	ds_read2st64_b32 v[14:15], v3 offset0:6 offset1:7
	ds_read2st64_b32 v[104:105], v3 offset0:8 offset1:9
	ds_read2st64_b32 v[106:107], v3 offset0:10 offset1:11
	ds_read2st64_b32 v[108:109], v3 offset0:12 offset1:13
	ds_read2st64_b32 v[110:111], v3 offset0:14 offset1:15
	ds_read2st64_b32 v[112:113], v3 offset0:16 offset1:17
	ds_read2st64_b32 v[114:115], v3 offset0:18 offset1:19
	ds_read2st64_b32 v[116:117], v3 offset0:20 offset1:21
	ds_read2st64_b32 v[118:119], v3 offset0:22 offset1:23
	ds_read2st64_b32 v[120:121], v3 offset0:24 offset1:25
	ds_read2st64_b32 v[122:123], v3 offset0:26 offset1:27
	ds_read2st64_b32 v[124:125], v3 offset0:28 offset1:29
	ds_read2st64_b32 v[126:127], v3 offset0:30 offset1:31
	ds_read2st64_b32 v[128:129], v3 offset0:32 offset1:33
	ds_read2st64_b32 v[130:131], v3 offset0:34 offset1:35
	ds_read2st64_b32 v[132:133], v3 offset0:36 offset1:37
	ds_read2st64_b32 v[134:135], v3 offset0:38 offset1:39
	ds_read2st64_b32 v[98:99], v3 offset0:40 offset1:41
	ds_read2st64_b32 v[136:137], v3 offset0:42 offset1:43
	ds_read2st64_b32 v[94:95], v3 offset0:44 offset1:45
	ds_read2st64_b32 v[96:97], v3 offset0:46 offset1:47
	ds_read2st64_b32 v[90:91], v3 offset0:48 offset1:49
	ds_read2st64_b32 v[92:93], v3 offset0:50 offset1:51
	ds_read2st64_b32 v[86:87], v3 offset0:52 offset1:53
	ds_read2st64_b32 v[88:89], v3 offset0:54 offset1:55
	ds_read2st64_b32 v[82:83], v3 offset0:56 offset1:57
	ds_read2st64_b32 v[84:85], v3 offset0:58 offset1:59
	ds_read2st64_b32 v[12:13], v3 offset0:60 offset1:61
	ds_read_b32 v80, v3 offset:15872
	s_waitcnt lgkmcnt(14)
	v_pk_mul_f32 v[10:11], v[208:209], v[10:11]
	v_pk_mul_f32 v[8:9], v[208:209], v[8:9]
	v_pk_fma_f32 v[10:11], v[64:65], v[0:1], v[10:11] op_sel_hi:[1,0,1] neg_lo:[0,0,1] neg_hi:[0,0,1]
	v_pk_fma_f32 v[8:9], v[66:67], v[0:1], v[8:9] op_sel_hi:[1,0,1] neg_lo:[0,0,1] neg_hi:[0,0,1]
	v_mul_f32_e32 v64, v11, v11
	v_pk_fma_f32 v[64:65], v[10:11], v[10:11], v[64:65] op_sel_hi:[1,1,0]
	v_mul_f32_e32 v66, v9, v9
	v_pk_fma_f32 v[64:65], v[8:9], v[8:9], v[64:65]
	v_pk_mul_f32 v[14:15], v[208:209], v[14:15]
	v_pk_add_f32 v[64:65], v[64:65], v[66:67] op_sel_hi:[1,0]
	v_pk_mul_f32 v[66:67], v[208:209], v[102:103]
	v_pk_fma_f32 v[14:15], v[70:71], v[0:1], v[14:15] op_sel_hi:[1,0,1] neg_lo:[0,0,1] neg_hi:[0,0,1]
	v_pk_fma_f32 v[66:67], v[68:69], v[0:1], v[66:67] op_sel_hi:[1,0,1] neg_lo:[0,0,1] neg_hi:[0,0,1]
	v_pk_mul_f32 v[70:71], v[208:209], v[104:105]
	v_pk_fma_f32 v[64:65], v[66:67], v[66:67], v[64:65]
	v_mul_f32_e32 v68, v67, v67
	v_pk_add_f32 v[64:65], v[64:65], v[68:69] op_sel_hi:[1,0]
	v_mul_f32_e32 v68, v15, v15
	v_pk_fma_f32 v[64:65], v[14:15], v[14:15], v[64:65]
	v_pk_fma_f32 v[70:71], v[72:73], v[0:1], v[70:71] op_sel_hi:[1,0,1] neg_lo:[0,0,1] neg_hi:[0,0,1]
	v_pk_add_f32 v[68:69], v[64:65], v[68:69] op_sel_hi:[1,0]
	v_pk_mul_f32 v[64:65], v[208:209], v[106:107]
	v_pk_fma_f32 v[68:69], v[70:71], v[70:71], v[68:69]
	v_mul_f32_e32 v72, v71, v71
	v_pk_fma_f32 v[64:65], v[74:75], v[0:1], v[64:65] op_sel_hi:[1,0,1] neg_lo:[0,0,1] neg_hi:[0,0,1]
	v_pk_add_f32 v[68:69], v[68:69], v[72:73] op_sel_hi:[1,0]
	v_mul_f32_e32 v72, v65, v65
	v_pk_fma_f32 v[68:69], v[64:65], v[64:65], v[68:69]
	s_or_b32 s0, s0, 0x3f00
	v_pk_add_f32 v[74:75], v[68:69], v[72:73] op_sel_hi:[1,0]
	v_pk_mul_f32 v[72:73], v[208:209], v[108:109]
	v_pk_mul_f32 v[68:69], v[208:209], v[110:111]
	v_pk_fma_f32 v[72:73], v[76:77], v[0:1], v[72:73] op_sel_hi:[1,0,1] neg_lo:[0,0,1] neg_hi:[0,0,1]
	v_pk_fma_f32 v[68:69], v[78:79], v[0:1], v[68:69] op_sel_hi:[1,0,1] neg_lo:[0,0,1] neg_hi:[0,0,1]
	v_pk_fma_f32 v[74:75], v[72:73], v[72:73], v[74:75]
	v_mul_f32_e32 v76, v73, v73
	v_pk_add_f32 v[74:75], v[74:75], v[76:77] op_sel_hi:[1,0]
	v_mul_f32_e32 v76, v69, v69
	v_pk_fma_f32 v[74:75], v[68:69], v[68:69], v[74:75]
	v_add_u32_e32 v2, s0, v2
	v_pk_add_f32 v[76:77], v[74:75], v[76:77] op_sel_hi:[1,0]
	v_pk_mul_f32 v[74:75], v[208:209], v[114:115]
	v_readlane_b32 s10, v254, 34
	v_pk_fma_f32 v[50:51], v[50:51], v[0:1], v[74:75] op_sel_hi:[1,0,1] neg_lo:[0,0,1] neg_hi:[0,0,1]
	v_pk_mul_f32 v[74:75], v[208:209], v[112:113]
	ds_read_b32 v81, v2
	v_pk_fma_f32 v[74:75], v[48:49], v[0:1], v[74:75] op_sel_hi:[1,0,1] neg_lo:[0,0,1] neg_hi:[0,0,1]
	v_lshlrev_b64 v[2:3], 11, v[210:211]
	v_pk_fma_f32 v[48:49], v[74:75], v[74:75], v[76:77]
	v_mul_f32_e32 v76, v75, v75
	v_readlane_b32 s11, v254, 35
	v_lshlrev_b32_e32 v100, 2, v225
	v_pk_add_f32 v[48:49], v[48:49], v[76:77] op_sel_hi:[1,0]
	v_lshl_add_u64 v[6:7], s[10:11], 0, v[2:3]
	global_load_dwordx4 v[2:5], v100, s[42:43]
	global_load_dwordx4 v[108:111], v100, s[42:43] offset:32
	global_load_dwordx4 v[112:115], v100, s[42:43] offset:64
	global_load_dwordx4 v[164:167], v100, s[42:43] offset:96
	global_load_dwordx4 v[168:171], v100, s[42:43] offset:128
	global_load_dwordx4 v[184:187], v100, s[42:43] offset:160
	global_load_dwordx4 v[188:191], v100, s[42:43] offset:192
	global_load_dwordx4 v[192:195], v100, s[42:43] offset:224
	global_load_dwordx4 v[196:199], v100, s[42:43] offset:256
	global_load_dwordx4 v[200:203], v100, s[42:43] offset:288
	global_load_dwordx4 v[228:231], v100, s[42:43] offset:320
	global_load_dwordx4 v[232:235], v100, s[42:43] offset:352
	global_load_dwordx4 v[236:239], v100, s[42:43] offset:384
	global_load_dwordx4 v[240:243], v100, s[42:43] offset:416
	global_load_dwordx4 v[244:247], v100, s[42:43] offset:448
	global_load_dwordx4 v[248:251], v100, s[42:43] offset:480
	v_pk_fma_f32 v[48:49], v[50:51], v[50:51], v[48:49]
	v_mul_f32_e32 v76, v51, v51
	v_pk_add_f32 v[76:77], v[48:49], v[76:77] op_sel_hi:[1,0]
	v_pk_mul_f32 v[48:49], v[208:209], v[118:119]
	s_waitcnt lgkmcnt(2)
; template <bool FAST> __device__ __forceinline__ bool attn_unit(LAS unsigned char* lds, const bf16_t* QKV, bf16_t* O, int qrow0, int b, int h, int nt, float lam, float oscale, const float* subln_g) {
;     ...
;         float ss = 0.f;
; #pragma unroll
;         for (int c = 0; c < 4; ++c)
; #pragma unroll
;             for (int i = 0; i < 16; ++i) { const float v = o[c][i] * inv - lam * ex[((wq * 64) + c * 16 + i) * 64 + lane]; o[c][i] = v; ss += v * v; }
	v_pk_mul_f32 v[12:13], v[208:209], v[12:13]
	v_pk_fma_f32 v[48:49], v[54:55], v[0:1], v[48:49] op_sel_hi:[1,0,1] neg_lo:[0,0,1] neg_hi:[0,0,1]
	v_pk_mul_f32 v[54:55], v[208:209], v[116:117]
	v_pk_fma_f32 v[12:13], v[28:29], v[0:1], v[12:13] op_sel_hi:[1,0,1] neg_lo:[0,0,1] neg_hi:[0,0,1]
	v_pk_fma_f32 v[54:55], v[52:53], v[0:1], v[54:55] op_sel_hi:[1,0,1] neg_lo:[0,0,1] neg_hi:[0,0,1]
	s_lshl_b32 s0, s71, 1
	v_pk_fma_f32 v[52:53], v[54:55], v[54:55], v[76:77]
	v_mul_f32_e32 v76, v55, v55
	v_pk_add_f32 v[52:53], v[52:53], v[76:77] op_sel_hi:[1,0]
	v_mul_f32_e32 v76, v49, v49
	v_pk_fma_f32 v[52:53], v[48:49], v[48:49], v[52:53]
	v_lshl_add_u64 v[6:7], v[6:7], 0, s[0:1]
	v_pk_add_f32 v[76:77], v[52:53], v[76:77] op_sel_hi:[1,0]
	v_pk_mul_f32 v[52:53], v[208:209], v[122:123]
	s_nop 0
	v_pk_fma_f32 v[52:53], v[58:59], v[0:1], v[52:53] op_sel_hi:[1,0,1] neg_lo:[0,0,1] neg_hi:[0,0,1]
	v_pk_mul_f32 v[58:59], v[208:209], v[120:121]
	s_nop 0
	v_pk_fma_f32 v[58:59], v[56:57], v[0:1], v[58:59] op_sel_hi:[1,0,1] neg_lo:[0,0,1] neg_hi:[0,0,1]
	s_nop 0
	v_pk_fma_f32 v[56:57], v[58:59], v[58:59], v[76:77]
	v_mul_f32_e32 v76, v59, v59
	v_pk_add_f32 v[56:57], v[56:57], v[76:77] op_sel_hi:[1,0]
	v_mul_f32_e32 v76, v53, v53
	v_pk_fma_f32 v[56:57], v[52:53], v[52:53], v[56:57]
	s_nop 0
	v_pk_add_f32 v[76:77], v[56:57], v[76:77] op_sel_hi:[1,0]
	v_pk_mul_f32 v[56:57], v[208:209], v[126:127]
	s_nop 0
	v_pk_fma_f32 v[56:57], v[62:63], v[0:1], v[56:57] op_sel_hi:[1,0,1] neg_lo:[0,0,1] neg_hi:[0,0,1]
	v_pk_mul_f32 v[62:63], v[208:209], v[124:125]
	s_nop 0
	v_pk_fma_f32 v[60:61], v[60:61], v[0:1], v[62:63] op_sel_hi:[1,0,1] neg_lo:[0,0,1] neg_hi:[0,0,1]
	s_nop 0
	v_pk_fma_f32 v[62:63], v[60:61], v[60:61], v[76:77]
	v_mul_f32_e32 v76, v61, v61
	v_pk_add_f32 v[62:63], v[62:63], v[76:77] op_sel_hi:[1,0]
	v_mul_f32_e32 v76, v57, v57
	v_pk_fma_f32 v[62:63], v[56:57], v[56:57], v[62:63]
	s_nop 0
	v_pk_add_f32 v[76:77], v[62:63], v[76:77] op_sel_hi:[1,0]
	v_pk_mul_f32 v[62:63], v[208:209], v[130:131]
	s_nop 0
	v_pk_fma_f32 v[34:35], v[34:35], v[0:1], v[62:63] op_sel_hi:[1,0,1] neg_lo:[0,0,1] neg_hi:[0,0,1]
	v_pk_mul_f32 v[62:63], v[208:209], v[128:129]
	s_nop 0
	v_pk_fma_f32 v[62:63], v[32:33], v[0:1], v[62:63] op_sel_hi:[1,0,1] neg_lo:[0,0,1] neg_hi:[0,0,1]
	s_nop 0
	v_pk_fma_f32 v[32:33], v[62:63], v[62:63], v[76:77]
	v_mul_f32_e32 v76, v63, v63
	v_pk_add_f32 v[32:33], v[32:33], v[76:77] op_sel_hi:[1,0]
	v_mul_f32_e32 v76, v35, v35
	v_pk_fma_f32 v[32:33], v[34:35], v[34:35], v[32:33]
	s_nop 0
	v_pk_add_f32 v[76:77], v[32:33], v[76:77] op_sel_hi:[1,0]
	v_pk_mul_f32 v[32:33], v[208:209], v[134:135]
	s_nop 0
	v_pk_fma_f32 v[32:33], v[38:39], v[0:1], v[32:33] op_sel_hi:[1,0,1] neg_lo:[0,0,1] neg_hi:[0,0,1]
	v_pk_mul_f32 v[38:39], v[208:209], v[132:133]
	s_nop 0
	v_pk_fma_f32 v[38:39], v[36:37], v[0:1], v[38:39] op_sel_hi:[1,0,1] neg_lo:[0,0,1] neg_hi:[0,0,1]
	s_nop 0
	v_pk_fma_f32 v[36:37], v[38:39], v[38:39], v[76:77]
	v_mul_f32_e32 v76, v39, v39
	v_pk_add_f32 v[36:37], v[36:37], v[76:77] op_sel_hi:[1,0]
	v_mul_f32_e32 v76, v33, v33
	v_pk_fma_f32 v[36:37], v[32:33], v[32:33], v[36:37]
	s_nop 0
	v_pk_add_f32 v[76:77], v[36:37], v[76:77] op_sel_hi:[1,0]
	v_pk_mul_f32 v[36:37], v[208:209], v[136:137]
	s_nop 0
	v_pk_fma_f32 v[36:37], v[42:43], v[0:1], v[36:37] op_sel_hi:[1,0,1] neg_lo:[0,0,1] neg_hi:[0,0,1]
	v_pk_mul_f32 v[42:43], v[208:209], v[98:99]
	s_nop 0
	v_pk_fma_f32 v[42:43], v[40:41], v[0:1], v[42:43] op_sel_hi:[1,0,1] neg_lo:[0,0,1] neg_hi:[0,0,1]
	s_nop 0
	v_pk_fma_f32 v[40:41], v[42:43], v[42:43], v[76:77]
	v_mul_f32_e32 v76, v43, v43
	v_pk_add_f32 v[40:41], v[40:41], v[76:77] op_sel_hi:[1,0]
	v_mul_f32_e32 v76, v37, v37
	v_pk_fma_f32 v[40:41], v[36:37], v[36:37], v[40:41]
	s_nop 0
	v_pk_add_f32 v[76:77], v[40:41], v[76:77] op_sel_hi:[1,0]
	v_pk_mul_f32 v[40:41], v[208:209], v[96:97]
	s_nop 0
	v_pk_fma_f32 v[40:41], v[46:47], v[0:1], v[40:41] op_sel_hi:[1,0,1] neg_lo:[0,0,1] neg_hi:[0,0,1]
	v_pk_mul_f32 v[46:47], v[208:209], v[94:95]
	s_nop 0
	v_pk_fma_f32 v[44:45], v[44:45], v[0:1], v[46:47] op_sel_hi:[1,0,1] neg_lo:[0,0,1] neg_hi:[0,0,1]
	s_nop 0
	v_pk_fma_f32 v[46:47], v[44:45], v[44:45], v[76:77]
	v_mul_f32_e32 v76, v45, v45
	v_pk_add_f32 v[46:47], v[46:47], v[76:77] op_sel_hi:[1,0]
	v_mul_f32_e32 v76, v41, v41
	v_pk_fma_f32 v[46:47], v[40:41], v[40:41], v[46:47]
	s_nop 0
	v_pk_add_f32 v[46:47], v[46:47], v[76:77] op_sel_hi:[1,0]
	v_pk_mul_f32 v[76:77], v[208:209], v[92:93]
	s_nop 0
	v_pk_fma_f32 v[18:19], v[18:19], v[0:1], v[76:77] op_sel_hi:[1,0,1] neg_lo:[0,0,1] neg_hi:[0,0,1]
	v_pk_mul_f32 v[76:77], v[208:209], v[90:91]
	s_nop 0
	v_pk_fma_f32 v[16:17], v[16:17], v[0:1], v[76:77] op_sel_hi:[1,0,1] neg_lo:[0,0,1] neg_hi:[0,0,1]
	s_nop 0
	v_pk_fma_f32 v[46:47], v[16:17], v[16:17], v[46:47]
	v_mul_f32_e32 v76, v17, v17
	v_pk_add_f32 v[46:47], v[46:47], v[76:77] op_sel_hi:[1,0]
	v_mul_f32_e32 v76, v19, v19
	v_pk_fma_f32 v[46:47], v[18:19], v[18:19], v[46:47]
	s_nop 0
	v_pk_add_f32 v[46:47], v[46:47], v[76:77] op_sel_hi:[1,0]
	v_pk_mul_f32 v[76:77], v[208:209], v[88:89]
	s_nop 0
	v_pk_fma_f32 v[22:23], v[22:23], v[0:1], v[76:77] op_sel_hi:[1,0,1] neg_lo:[0,0,1] neg_hi:[0,0,1]
	v_pk_mul_f32 v[76:77], v[208:209], v[86:87]
	s_nop 0
	v_pk_fma_f32 v[20:21], v[20:21], v[0:1], v[76:77] op_sel_hi:[1,0,1] neg_lo:[0,0,1] neg_hi:[0,0,1]
	s_nop 0
	v_pk_fma_f32 v[46:47], v[20:21], v[20:21], v[46:47]
	v_mul_f32_e32 v76, v21, v21
	v_pk_add_f32 v[46:47], v[46:47], v[76:77] op_sel_hi:[1,0]
	v_mul_f32_e32 v76, v23, v23
	v_pk_fma_f32 v[46:47], v[22:23], v[22:23], v[46:47]
	s_nop 0
	v_pk_add_f32 v[46:47], v[46:47], v[76:77] op_sel_hi:[1,0]
	v_pk_mul_f32 v[76:77], v[208:209], v[84:85]
	s_nop 0
	v_pk_fma_f32 v[26:27], v[26:27], v[0:1], v[76:77] op_sel_hi:[1,0,1] neg_lo:[0,0,1] neg_hi:[0,0,1]
	v_pk_mul_f32 v[76:77], v[208:209], v[82:83]
	s_nop 0
	v_pk_fma_f32 v[24:25], v[24:25], v[0:1], v[76:77] op_sel_hi:[1,0,1] neg_lo:[0,0,1] neg_hi:[0,0,1]
	s_nop 0
	v_pk_fma_f32 v[46:47], v[24:25], v[24:25], v[46:47]
	v_mul_f32_e32 v76, v25, v25
	v_pk_add_f32 v[46:47], v[46:47], v[76:77] op_sel_hi:[1,0]
	v_mul_f32_e32 v76, v27, v27
	v_pk_fma_f32 v[46:47], v[26:27], v[26:27], v[46:47]
	s_nop 0
	v_pk_add_f32 v[46:47], v[46:47], v[76:77] op_sel_hi:[1,0]
	s_waitcnt lgkmcnt(0)
; __device__ __forceinline__ unsigned cvt_pk_bf16(float lo, float hi) { f32x2 v = {lo, hi}; bf16x2_t b = __builtin_convertvector(v, bf16x2_t); return __builtin_bit_cast(unsigned, b); }
; __device__ __forceinline__ float swap32_sum(float m) { auto rr = __builtin_amdgcn_permlane32_swap(__float_as_uint(m), __float_as_uint(m), false, false); return __uint_as_float(rr[0]) + __uint_as_float(rr[1]); }
; template <bool FAST> __device__ __forceinline__ bool attn_unit(LAS unsigned char* lds, const bf16_t* QKV, bf16_t* O, int qrow0, int b, int h, int nt, float lam, float oscale, const float* subln_g) {
;     ...
;         ss = swap32_sum(ss);
;         const float r = rsqrtf(ss * (1.f / 128.f) + EPS) * oscale;
;         bf16_t* op = O + (size_t)(qrow0 + wq * 32 + r32) * D + h * 128;
; #pragma unroll
;         for (int c = 0; c < 4; ++c)
; #pragma unroll
;             for (int g4 = 0; g4 < 4; ++g4) { const int d = 32 * c + 8 * g4 + 4 * hi; const f32x4 gv = *(const f32x4*)(subln_g + d);
;                 u32x2 w; w.x = cvt_pk_bf16(o[c][4 * g4] * r * gv[0], o[c][4 * g4 + 1] * r * gv[1]); w.y = cvt_pk_bf16(o[c][4 * g4 + 2] * r * gv[2], o[c][4 * g4 + 3] * r * gv[3]);
;                 *(u32x2*)(op + d) = w; }
	v_pk_mul_f32 v[76:77], v[208:209], v[80:81]
	v_pk_fma_f32 v[28:29], v[12:13], v[12:13], v[46:47]
	v_pk_fma_f32 v[30:31], v[30:31], v[0:1], v[76:77] op_sel_hi:[1,0,1] neg_lo:[0,0,1] neg_hi:[0,0,1]
	v_mul_f32_e32 v0, v13, v13
	v_pk_add_f32 v[28:29], v[28:29], v[0:1] op_sel_hi:[1,0]
	v_mul_f32_e32 v0, v31, v31
	v_pk_fma_f32 v[28:29], v[30:31], v[30:31], v[28:29]
	s_nop 0
	v_pk_add_f32 v[28:29], v[28:29], v[0:1] op_sel_hi:[1,0]
	s_nop 0
	v_mov_b32_e32 v0, v28
	s_nop 1
	v_permlane32_swap_b32_e32 v28, v0
	v_add_f32_e32 v0, v28, v0
	v_fmamk_f32 v0, v0, 0x3c000000, v215
	v_mul_f32_e32 v28, 0x4b800000, v0
	v_cmp_gt_f32_e32 vcc, s87, v0
	s_nop 1
	v_cndmask_b32_e32 v0, v0, v28, vcc
	v_rsq_f32_e32 v28, v0
	v_lshlrev_b32_e32 v0, 1, v225
	v_lshl_add_u64 v[6:7], v[6:7], 0, v[0:1]
	v_mul_f32_e32 v0, 0x45800000, v28
	v_cndmask_b32_e32 v0, v28, v0, vcc
	v_mul_f32_e32 v0, v224, v0
	v_pk_mul_f32 v[10:11], v[10:11], v[0:1] op_sel_hi:[1,0]
	v_pk_mul_f32 v[8:9], v[8:9], v[0:1] op_sel_hi:[1,0]
	s_waitcnt vmcnt(0)
	v_pk_mul_f32 v[2:3], v[2:3], v[10:11]
	v_pk_mul_f32 v[4:5], v[4:5], v[8:9]
	v_cvt_pk_bf16_f32 v2, v2, v3
	v_cvt_pk_bf16_f32 v3, v4, v5
	global_store_dwordx2 v[6:7], v[2:3], off
	v_mov_b64_e32 v[2:3], v[108:109]
	v_mov_b64_e32 v[4:5], v[110:111]
	v_pk_mul_f32 v[8:9], v[66:67], v[0:1] op_sel_hi:[1,0]
	v_pk_mul_f32 v[10:11], v[64:65], v[0:1] op_sel_hi:[1,0]
	v_pk_mul_f32 v[2:3], v[2:3], v[8:9]
	v_pk_mul_f32 v[8:9], v[14:15], v[0:1] op_sel_hi:[1,0]
	v_cvt_pk_bf16_f32 v2, v2, v3
	v_pk_mul_f32 v[4:5], v[4:5], v[8:9]
	v_pk_mul_f32 v[8:9], v[70:71], v[0:1] op_sel_hi:[1,0]
	v_cvt_pk_bf16_f32 v3, v4, v5
	global_store_dwordx2 v[6:7], v[2:3], off offset:16
	v_mov_b64_e32 v[2:3], v[112:113]
	v_mov_b64_e32 v[4:5], v[114:115]
	v_pk_mul_f32 v[2:3], v[2:3], v[8:9]
	v_pk_mul_f32 v[4:5], v[4:5], v[10:11]
	v_cvt_pk_bf16_f32 v2, v2, v3
	v_cvt_pk_bf16_f32 v3, v4, v5
	global_store_dwordx2 v[6:7], v[2:3], off offset:32
	v_mov_b64_e32 v[2:3], v[164:165]
	v_mov_b64_e32 v[4:5], v[166:167]
	v_pk_mul_f32 v[8:9], v[72:73], v[0:1] op_sel_hi:[1,0]
	v_pk_mul_f32 v[10:11], v[68:69], v[0:1] op_sel_hi:[1,0]
	v_pk_mul_f32 v[2:3], v[2:3], v[8:9]
	v_pk_mul_f32 v[4:5], v[4:5], v[10:11]
	v_cvt_pk_bf16_f32 v2, v2, v3
	v_cvt_pk_bf16_f32 v3, v4, v5
	global_store_dwordx2 v[6:7], v[2:3], off offset:48
	v_mov_b64_e32 v[2:3], v[168:169]
	v_mov_b64_e32 v[4:5], v[170:171]
	v_pk_mul_f32 v[8:9], v[74:75], v[0:1] op_sel_hi:[1,0]
	v_pk_mul_f32 v[10:11], v[50:51], v[0:1] op_sel_hi:[1,0]
	v_pk_mul_f32 v[2:3], v[2:3], v[8:9]
	v_pk_mul_f32 v[4:5], v[4:5], v[10:11]
	v_cvt_pk_bf16_f32 v2, v2, v3
	v_cvt_pk_bf16_f32 v3, v4, v5
	global_store_dwordx2 v[6:7], v[2:3], off offset:64
	v_mov_b64_e32 v[2:3], v[184:185]
	v_mov_b64_e32 v[4:5], v[186:187]
	v_pk_mul_f32 v[8:9], v[54:55], v[0:1] op_sel_hi:[1,0]
	v_pk_mul_f32 v[10:11], v[48:49], v[0:1] op_sel_hi:[1,0]
	v_pk_mul_f32 v[2:3], v[2:3], v[8:9]
	v_pk_mul_f32 v[4:5], v[4:5], v[10:11]
	v_cvt_pk_bf16_f32 v2, v2, v3
	v_cvt_pk_bf16_f32 v3, v4, v5
	global_store_dwordx2 v[6:7], v[2:3], off offset:80
	v_mov_b64_e32 v[2:3], v[188:189]
	v_mov_b64_e32 v[4:5], v[190:191]
	v_pk_mul_f32 v[8:9], v[58:59], v[0:1] op_sel_hi:[1,0]
	v_pk_mul_f32 v[10:11], v[52:53], v[0:1] op_sel_hi:[1,0]
	v_pk_mul_f32 v[2:3], v[8:9], v[2:3]
	v_pk_mul_f32 v[4:5], v[10:11], v[4:5]
	v_cvt_pk_bf16_f32 v2, v2, v3
	v_cvt_pk_bf16_f32 v3, v4, v5
	global_store_dwordx2 v[6:7], v[2:3], off offset:96
	v_mov_b64_e32 v[2:3], v[192:193]
	v_mov_b64_e32 v[4:5], v[194:195]
	v_pk_mul_f32 v[8:9], v[60:61], v[0:1] op_sel_hi:[1,0]
	v_pk_mul_f32 v[10:11], v[56:57], v[0:1] op_sel_hi:[1,0]
	v_pk_mul_f32 v[2:3], v[8:9], v[2:3]
	v_pk_mul_f32 v[4:5], v[10:11], v[4:5]
	v_cvt_pk_bf16_f32 v2, v2, v3
	v_cvt_pk_bf16_f32 v3, v4, v5
	global_store_dwordx2 v[6:7], v[2:3], off offset:112
	v_mov_b64_e32 v[2:3], v[196:197]
	v_mov_b64_e32 v[4:5], v[198:199]
	v_pk_mul_f32 v[8:9], v[62:63], v[0:1] op_sel_hi:[1,0]
	v_pk_mul_f32 v[10:11], v[34:35], v[0:1] op_sel_hi:[1,0]
	v_pk_mul_f32 v[2:3], v[8:9], v[2:3]
	v_pk_mul_f32 v[4:5], v[10:11], v[4:5]
	v_cvt_pk_bf16_f32 v2, v2, v3
	v_cvt_pk_bf16_f32 v3, v4, v5
	global_store_dwordx2 v[6:7], v[2:3], off offset:128
	v_mov_b64_e32 v[2:3], v[200:201]
	v_mov_b64_e32 v[4:5], v[202:203]
	v_pk_mul_f32 v[8:9], v[38:39], v[0:1] op_sel_hi:[1,0]
	v_pk_mul_f32 v[10:11], v[32:33], v[0:1] op_sel_hi:[1,0]
	v_pk_mul_f32 v[2:3], v[8:9], v[2:3]
	v_pk_mul_f32 v[4:5], v[10:11], v[4:5]
	v_cvt_pk_bf16_f32 v2, v2, v3
	v_cvt_pk_bf16_f32 v3, v4, v5
	global_store_dwordx2 v[6:7], v[2:3], off offset:144
	v_mov_b64_e32 v[2:3], v[228:229]
	v_mov_b64_e32 v[4:5], v[230:231]
	v_pk_mul_f32 v[8:9], v[42:43], v[0:1] op_sel_hi:[1,0]
	v_pk_mul_f32 v[10:11], v[36:37], v[0:1] op_sel_hi:[1,0]
	v_pk_mul_f32 v[2:3], v[8:9], v[2:3]
	v_pk_mul_f32 v[4:5], v[10:11], v[4:5]
	v_cvt_pk_bf16_f32 v2, v2, v3
	v_cvt_pk_bf16_f32 v3, v4, v5
	global_store_dwordx2 v[6:7], v[2:3], off offset:160
	v_mov_b64_e32 v[2:3], v[232:233]
	v_mov_b64_e32 v[4:5], v[234:235]
	v_pk_mul_f32 v[8:9], v[44:45], v[0:1] op_sel_hi:[1,0]
	v_pk_mul_f32 v[10:11], v[40:41], v[0:1] op_sel_hi:[1,0]
	v_pk_mul_f32 v[2:3], v[8:9], v[2:3]
	v_pk_mul_f32 v[4:5], v[10:11], v[4:5]
	v_cvt_pk_bf16_f32 v2, v2, v3
	v_cvt_pk_bf16_f32 v3, v4, v5
	global_store_dwordx2 v[6:7], v[2:3], off offset:176
	v_mov_b64_e32 v[2:3], v[236:237]
	v_mov_b64_e32 v[4:5], v[238:239]
	v_pk_mul_f32 v[8:9], v[16:17], v[0:1] op_sel_hi:[1,0]
	v_pk_mul_f32 v[10:11], v[18:19], v[0:1] op_sel_hi:[1,0]
	v_pk_mul_f32 v[2:3], v[8:9], v[2:3]
	v_pk_mul_f32 v[4:5], v[10:11], v[4:5]
	v_cvt_pk_bf16_f32 v2, v2, v3
	v_cvt_pk_bf16_f32 v3, v4, v5
	global_store_dwordx2 v[6:7], v[2:3], off offset:192
	v_mov_b64_e32 v[2:3], v[240:241]
	v_mov_b64_e32 v[4:5], v[242:243]
	v_pk_mul_f32 v[8:9], v[20:21], v[0:1] op_sel_hi:[1,0]
	v_pk_mul_f32 v[10:11], v[22:23], v[0:1] op_sel_hi:[1,0]
	v_pk_mul_f32 v[2:3], v[8:9], v[2:3]
	v_pk_mul_f32 v[4:5], v[10:11], v[4:5]
	v_cvt_pk_bf16_f32 v2, v2, v3
	v_cvt_pk_bf16_f32 v3, v4, v5
	global_store_dwordx2 v[6:7], v[2:3], off offset:208
	v_mov_b64_e32 v[2:3], v[244:245]
	v_mov_b64_e32 v[4:5], v[246:247]
	v_pk_mul_f32 v[8:9], v[24:25], v[0:1] op_sel_hi:[1,0]
	v_pk_mul_f32 v[10:11], v[26:27], v[0:1] op_sel_hi:[1,0]
	v_pk_mul_f32 v[2:3], v[8:9], v[2:3]
	v_pk_mul_f32 v[4:5], v[10:11], v[4:5]
	v_cvt_pk_bf16_f32 v2, v2, v3
	v_cvt_pk_bf16_f32 v3, v4, v5
	global_store_dwordx2 v[6:7], v[2:3], off offset:224
	v_mov_b64_e32 v[2:3], v[248:249]
	v_mov_b64_e32 v[4:5], v[250:251]
	v_pk_mul_f32 v[8:9], v[12:13], v[0:1] op_sel_hi:[1,0]
	v_pk_mul_f32 v[10:11], v[30:31], v[0:1] op_sel_hi:[1,0]
	v_pk_mul_f32 v[2:3], v[8:9], v[2:3]
	v_pk_mul_f32 v[4:5], v[10:11], v[4:5]
	v_cvt_pk_bf16_f32 v2, v2, v3
	v_cvt_pk_bf16_f32 v3, v4, v5
	global_store_dwordx2 v[6:7], v[2:3], off offset:240
	s_branch .LBB0_268
